# cv53 + T2 thin_rows loop: counted waits at the head of each half instead of the vmcnt countdown ladder (same fix as T1)
# baseline (speedup 1.0000x reference)
.LBB0_1828:
	s_cmp_le_i32 s62, s6
	s_cselect_b64 s[0:1], -1, 0
	s_cmp_lt_i32 s6, s63
	s_cselect_b64 s[4:5], -1, 0
	s_and_b64 s[0:1], s[0:1], s[4:5]
	s_andn2_b64 vcc, exec, s[0:1]
	s_cbranch_vccnz .LBB0_1871
	v_readlane_b32 s4, v253, 3
	v_readlane_b32 s5, v253, 4
	v_mov_b32_e32 v17, v0
	s_waitcnt lgkmcnt(0)
	s_load_dwordx2 s[10:11], s[4:5], 0xa0
	s_load_dwordx4 s[44:47], s[4:5], 0xb8
	v_readlane_b32 s5, v253, 53
	v_readfirstlane_b32 s4, v17
	s_ashr_i32 s4, s4, 6
	s_add_i32 s34, s4, s5
	s_cmp_eq_u32 s30, 3
	s_cselect_b64 s[8:9], -1, 0
	s_lshl_b32 s20, s30, 11
	s_lshl_b64 s[4:5], s[20:21], 2
	s_waitcnt lgkmcnt(0)
	s_add_u32 s4, s10, s4
	s_waitcnt vmcnt(0)
	v_and_b32_e32 v140, 63, v17
	s_addc_u32 s5, s11, s5
	s_cmpk_gt_i32 s34, 0x1fff
	v_cmp_eq_u32_e64 s[38:39], 0, v140
	s_cbranch_scc1 .LBB0_1850
	s_add_u32 s12, s46, 0x20d00000
	s_addc_u32 s13, s47, 0
	s_add_u32 s6, s46, 0x47800000
	s_addc_u32 s14, s47, 0
	s_add_u32 s16, s46, 0x39400000
	s_addc_u32 s17, s47, 0
	s_and_b64 s[10:11], s[8:9], exec
	s_cselect_b32 s27, s45, 0
	s_cselect_b32 s26, s44, 0
	s_ashr_i32 s35, s34, 31
	s_lshl_b64 s[10:11], s[34:35], 12
	v_lshlrev_b32_e32 v34, 4, v140
	s_add_u32 s28, s16, s10
	v_or_b32_e32 v14, 0x1000, v34
	v_or_b32_e32 v15, 0x1400, v34
	s_addc_u32 s29, s17, s11
	global_load_dwordx4 v[2:5], v34, s[4:5]
	global_load_dwordx4 v[6:9], v34, s[4:5] offset:1024
	global_load_dwordx4 v[10:13], v34, s[4:5] offset:2048
	global_load_dwordx4 v[18:21], v34, s[4:5] offset:3072
	global_load_dwordx4 v[22:25], v14, s[4:5]
	global_load_dwordx4 v[26:29], v15, s[4:5]
	v_or_b32_e32 v14, 0x1800, v34
	v_or_b32_e32 v15, 0x1c00, v34
	s_add_u32 s10, s12, s10
	v_lshlrev_b32_e32 v40, 3, v140
	global_load_dwordx4 v[30:33], v14, s[4:5]
	global_load_dwordx4 v[36:39], v15, s[4:5]
	s_addc_u32 s11, s13, s11
	global_load_dwordx2 v[14:15], v40, s[28:29]
	global_load_dwordx2 v[72:73], v40, s[28:29] offset:512
	global_load_dwordx2 v[74:75], v40, s[28:29] offset:1024
	global_load_dwordx2 v[76:77], v40, s[28:29] offset:1536
	global_load_dwordx2 v[78:79], v40, s[28:29] offset:2048
	global_load_dwordx2 v[80:81], v40, s[28:29] offset:2560
	global_load_dwordx2 v[82:83], v40, s[28:29] offset:3072
	global_load_dwordx2 v[84:85], v40, s[28:29] offset:3584
	global_load_dwordx2 v[86:87], v40, s[10:11]
	global_load_dwordx2 v[88:89], v40, s[10:11] offset:512
	global_load_dwordx2 v[90:91], v40, s[10:11] offset:1024
	global_load_dwordx2 v[92:93], v40, s[10:11] offset:1536
	global_load_dwordx2 v[94:95], v40, s[10:11] offset:2048
	global_load_dwordx2 v[96:97], v40, s[10:11] offset:2560
	global_load_dwordx2 v[98:99], v40, s[10:11] offset:3072
	global_load_dwordx2 v[100:101], v40, s[10:11] offset:3584
	v_and_b32_e32 v42, 64, v213
	v_add_u32_e32 v42, 64, v42
	v_xor_b32_e32 v43, 1, v213
	v_cmp_lt_i32_e32 vcc, v43, v42
	v_mov_b32_e32 v41, v35
	s_cmp_lg_u64 s[26:27], 0
	v_cndmask_b32_e32 v43, v213, v43, vcc
	v_lshlrev_b32_e32 v141, 2, v43
	v_xor_b32_e32 v43, 2, v213
	v_cmp_lt_i32_e32 vcc, v43, v42
	v_lshl_add_u64 v[102:103], s[26:27], 0, v[34:35]
	v_mov_b32_e32 v34, v35
	v_cndmask_b32_e32 v43, v213, v43, vcc
	v_lshlrev_b32_e32 v142, 2, v43
	v_xor_b32_e32 v43, 4, v213
	v_cmp_lt_i32_e32 vcc, v43, v42
	s_cselect_b64 s[10:11], -1, 0
	v_lshl_add_u64 v[104:105], s[12:13], 0, v[40:41]
	v_cndmask_b32_e32 v43, v213, v43, vcc
	v_lshlrev_b32_e32 v143, 2, v43
	v_xor_b32_e32 v43, 8, v213
	v_cmp_lt_i32_e32 vcc, v43, v42
	v_lshl_add_u64 v[106:107], s[16:17], 0, v[40:41]
	v_mov_b64_e32 v[108:109], v[34:35]
	v_cndmask_b32_e32 v43, v213, v43, vcc
	v_lshlrev_b32_e32 v144, 2, v43
	v_xor_b32_e32 v43, 16, v213
	v_cmp_lt_i32_e32 vcc, v43, v42
	v_mov_b64_e32 v[110:111], v[34:35]
	v_mov_b64_e32 v[112:113], v[34:35]
	v_cndmask_b32_e32 v43, v213, v43, vcc
	v_lshlrev_b32_e32 v145, 2, v43
	v_xor_b32_e32 v43, 32, v213
	v_cmp_lt_i32_e32 vcc, v43, v42
	v_mov_b64_e32 v[114:115], v[34:35]
	v_mov_b64_e32 v[116:117], v[34:35]
	v_cndmask_b32_e32 v42, v213, v43, vcc
	v_lshlrev_b32_e32 v146, 2, v42
	v_mov_b64_e32 v[118:119], v[34:35]
	v_mov_b64_e32 v[120:121], v[34:35]
	v_mov_b64_e32 v[122:123], v[34:35]
	v_mov_b64_e32 v[124:125], v[34:35]
	v_mov_b64_e32 v[126:127], v[34:35]
	v_mov_b64_e32 v[128:129], v[34:35]
	v_mov_b64_e32 v[130:131], v[34:35]
	v_mov_b64_e32 v[132:133], v[34:35]
	v_mov_b64_e32 v[134:135], v[34:35]
	v_mov_b64_e32 v[136:137], v[34:35]
	v_mov_b64_e32 v[138:139], v[34:35]
	s_waitcnt vmcnt(0)
	s_branch .LBB0_1834

.LBB0_1833:
	s_waitcnt vmcnt(8)
	s_and_b64 vcc, exec, s[36:37]
	s_cbranch_vccnz .LBB0_1850

.LBB0_1836:
	v_and_b32_e32 v57, 0xffff0000, v72
	v_and_b32_e32 v56, 0xffff0000, v14
	v_and_b32_e32 v61, 0xffff0000, v73
	v_and_b32_e32 v60, 0xffff0000, v15
	v_lshlrev_b32_e32 v55, 16, v72
	v_lshlrev_b32_e32 v54, 16, v14
	v_lshlrev_b32_e32 v59, 16, v73
	v_lshlrev_b32_e32 v58, 16, v15
	v_pk_mul_f32 v[62:63], v[56:57], v[56:57]
	v_pk_mul_f32 v[64:65], v[60:61], v[60:61]
	v_pk_fma_f32 v[62:63], v[54:55], v[54:55], v[62:63]
	v_pk_fma_f32 v[64:65], v[58:59], v[58:59], v[64:65]
	v_and_b32_e32 v151, 0xffff0000, v75
	v_and_b32_e32 v150, 0xffff0000, v74
	v_lshlrev_b32_e32 v50, 16, v76
	v_and_b32_e32 v51, 0xffff0000, v76
	v_lshlrev_b32_e32 v48, 16, v78
	v_pk_add_f32 v[62:63], v[62:63], v[64:65]
	v_lshlrev_b32_e32 v149, 16, v75
	v_lshlrev_b32_e32 v148, 16, v74
	v_pk_mul_f32 v[64:65], v[150:151], v[150:151]
	v_lshlrev_b32_e32 v152, 16, v77
	v_pk_fma_f32 v[64:65], v[148:149], v[148:149], v[64:65]
	v_mul_f32_e32 v49, v50, v50
	v_mul_f32_e32 v67, v51, v51
	v_and_b32_e32 v153, 0xffff0000, v77
	v_mul_f32_e32 v34, v152, v152
	v_mov_b32_e32 v66, v48
	v_and_b32_e32 v147, 0xffff0000, v78
	v_lshlrev_b32_e32 v46, 16, v79
	v_and_b32_e32 v47, 0xffff0000, v79
	v_pk_add_f32 v[62:63], v[62:63], v[62:63] op_sel_hi:[0,1]
	v_pk_add_f32 v[64:65], v[64:65], v[64:65] op_sel_hi:[0,1]
	v_pk_fma_f32 v[68:69], v[152:153], v[152:153], v[34:35] op_sel_hi:[1,1,0]
	v_pk_add_f32 v[66:67], v[48:49], v[66:67]
	v_mul_f32_e32 v68, v147, v147
	v_mul_f32_e32 v64, v46, v46
	v_mul_f32_e32 v62, v47, v47
	v_mul_f32_e32 v70, v48, v48
	v_mov_b32_e32 v71, v67
	v_and_b32_e32 v157, 0xffff0000, v81
	v_and_b32_e32 v156, 0xffff0000, v80
	v_lshlrev_b32_e32 v44, 16, v82
	v_and_b32_e32 v45, 0xffff0000, v82
	v_lshlrev_b32_e32 v42, 16, v84
	v_pk_add_f32 v[66:67], v[70:71], v[68:69]
	v_pk_add_f32 v[62:63], v[64:65], v[62:63]
	v_lshlrev_b32_e32 v155, 16, v81
	v_lshlrev_b32_e32 v154, 16, v80
	v_pk_mul_f32 v[64:65], v[156:157], v[156:157]
	v_lshlrev_b32_e32 v158, 16, v83
	v_pk_add_f32 v[62:63], v[66:67], v[62:63]
	v_pk_fma_f32 v[64:65], v[154:155], v[154:155], v[64:65]
	v_mul_f32_e32 v43, v44, v44
	v_mul_f32_e32 v67, v45, v45
	v_and_b32_e32 v159, 0xffff0000, v83
	v_mul_f32_e32 v34, v158, v158
	v_mov_b32_e32 v66, v42
	v_and_b32_e32 v183, 0xffff0000, v84
	s_waitcnt lgkmcnt(0)
	v_lshlrev_b32_e32 v40, 16, v85
	v_and_b32_e32 v41, 0xffff0000, v85
	v_pk_add_f32 v[62:63], v[62:63], v[62:63] op_sel_hi:[0,1]
	v_pk_add_f32 v[64:65], v[64:65], v[64:65] op_sel_hi:[0,1]
	v_pk_fma_f32 v[68:69], v[158:159], v[158:159], v[34:35] op_sel_hi:[1,1,0]
	v_pk_add_f32 v[66:67], v[42:43], v[66:67]
	v_mul_f32_e32 v68, v183, v183
	v_mul_f32_e32 v64, v40, v40
	v_mul_f32_e32 v62, v41, v41
	v_mul_f32_e32 v70, v42, v42
	v_mov_b32_e32 v71, v67
	v_pk_add_f32 v[66:67], v[70:71], v[68:69]
	v_pk_add_f32 v[62:63], v[64:65], v[62:63]
	s_ashr_i32 s35, s34, 31
	v_pk_add_f32 v[62:63], v[66:67], v[62:63]
	s_lshl_b64 s[42:43], s[34:35], 11
	v_add_f32_e32 v34, v62, v63
	ds_bpermute_b32 v43, v141, v34
	s_lshl_b64 s[16:17], s[34:35], 2
	s_add_u32 s28, s6, s16
	s_addc_u32 s29, s14, s17
	v_lshlrev_b32_e32 v52, 16, v86
	s_waitcnt lgkmcnt(0)
	v_add_f32_e32 v34, v34, v43
	ds_bpermute_b32 v43, v142, v34
	v_and_b32_e32 v53, 0xffff0000, v86
	v_lshlrev_b32_e32 v64, 16, v88
	v_and_b32_e32 v65, 0xffff0000, v88
	v_mov_b32_e32 v71, v60
	s_waitcnt lgkmcnt(0)
	v_add_f32_e32 v34, v34, v43
	ds_bpermute_b32 v43, v143, v34
	v_mov_b32_e32 v60, v59
	v_lshlrev_b32_e32 v66, 16, v89
	v_and_b32_e32 v67, 0xffff0000, v89
	v_lshlrev_b32_e32 v62, 16, v87
	s_waitcnt lgkmcnt(0)
	v_add_f32_e32 v34, v34, v43
	ds_bpermute_b32 v43, v144, v34
	v_and_b32_e32 v63, 0xffff0000, v87
	v_lshlrev_b32_e32 v160, 16, v90
	v_and_b32_e32 v161, 0xffff0000, v90
	v_lshlrev_b32_e32 v162, 16, v91
	s_waitcnt lgkmcnt(0)
	v_add_f32_e32 v34, v34, v43
	ds_bpermute_b32 v43, v145, v34
	v_and_b32_e32 v163, 0xffff0000, v91
	v_lshlrev_b32_e32 v170, 16, v95
	v_and_b32_e32 v171, 0xffff0000, v95
	v_lshlrev_b32_e32 v166, 16, v93
	s_waitcnt lgkmcnt(0)
	v_add_f32_e32 v34, v34, v43
	ds_bpermute_b32 v43, v146, v34
	v_and_b32_e32 v167, 0xffff0000, v93
	v_lshlrev_b32_e32 v168, 16, v94
	v_and_b32_e32 v169, 0xffff0000, v94
	v_lshlrev_b32_e32 v164, 16, v92
	s_waitcnt lgkmcnt(0)
	v_add_f32_e32 v34, v34, v43
	v_fmamk_f32 v34, v34, 0x3a000000, v209
	v_mul_f32_e32 v43, 0x4f800000, v34
	v_cmp_gt_f32_e32 vcc, s33, v34
	v_and_b32_e32 v165, 0xffff0000, v92
	v_lshlrev_b32_e32 v172, 16, v96
	v_cndmask_b32_e32 v34, v34, v43, vcc
	v_sqrt_f32_e32 v43, v34
	v_and_b32_e32 v173, 0xffff0000, v96
	v_lshlrev_b32_e32 v174, 16, v97
	v_and_b32_e32 v175, 0xffff0000, v97
	v_add_u32_e32 v49, -1, v43
	v_fma_f32 v68, -v49, v43, v34
	v_cmp_ge_f32_e64 s[40:41], 0, v68
	v_add_u32_e32 v68, 1, v43
	v_lshlrev_b32_e32 v176, 16, v98
	v_cndmask_b32_e64 v49, v43, v49, s[40:41]
	v_fma_f32 v43, -v68, v43, v34
	v_cmp_lt_f32_e64 s[40:41], 0, v43
	v_and_b32_e32 v177, 0xffff0000, v98
	v_lshlrev_b32_e32 v184, 16, v99
	v_cndmask_b32_e64 v43, v49, v68, s[40:41]
	v_mul_f32_e32 v49, 0x37800000, v43
	v_cndmask_b32_e32 v43, v43, v49, vcc
	v_cmp_class_f32_e32 vcc, v34, v210
	v_and_b32_e32 v185, 0xffff0000, v99
	v_lshlrev_b32_e32 v186, 16, v100
	v_cndmask_b32_e32 v34, v43, v34, vcc
	v_div_scale_f32 v43, s[16:17], v34, v34, 1.0
	v_rcp_f32_e32 v49, v43
	v_and_b32_e32 v187, 0xffff0000, v100
	v_lshlrev_b32_e32 v188, 16, v101
	v_and_b32_e32 v189, 0xffff0000, v101
	v_fma_f32 v68, -v43, v49, 1.0
	v_fmac_f32_e32 v49, v68, v49
	v_div_scale_f32 v68, vcc, 1.0, v34, 1.0
	v_mul_f32_e32 v69, v68, v49
	v_fma_f32 v70, -v43, v69, v68
	v_fmac_f32_e32 v69, v70, v49
	v_fma_f32 v43, -v43, v69, v68
	v_div_fmas_f32 v43, v43, v49, v69
	v_div_fixup_f32 v34, v43, v34, 1.0
	v_mov_b32_e32 v68, v54
	v_mov_b32_e32 v69, v56
	v_pk_mul_f32 v[68:69], v[34:35], v[68:69] op_sel_hi:[0,1]
	v_mov_b32_e32 v56, v55
	v_pk_fma_f32 v[68:69], v[2:3], v[68:69], v[52:53]
	v_pk_mul_f32 v[52:53], v[34:35], v[56:57] op_sel_hi:[0,1]
	v_mov_b32_e32 v70, v58
	v_pk_mul_f32 v[54:55], v[34:35], v[60:61] op_sel_hi:[0,1]
	v_pk_fma_f32 v[64:65], v[6:7], v[52:53], v[64:65]
	v_mov_b32_e32 v52, v148
	v_mov_b32_e32 v53, v150
	v_mov_b32_e32 v150, v149
	v_pk_mul_f32 v[70:71], v[34:35], v[70:71] op_sel_hi:[0,1]
	v_pk_fma_f32 v[66:67], v[8:9], v[54:55], v[66:67]
	v_pk_mul_f32 v[52:53], v[34:35], v[52:53] op_sel_hi:[0,1]
	v_pk_mul_f32 v[54:55], v[34:35], v[150:151] op_sel_hi:[0,1]
	v_mov_b32_e32 v49, v147
	v_pk_mul_f32 v[46:47], v[34:35], v[46:47] op_sel_hi:[0,1]
	v_pk_fma_f32 v[70:71], v[4:5], v[70:71], v[62:63]
	v_pk_fma_f32 v[62:63], v[12:13], v[54:55], v[162:163]
	v_pk_fma_f32 v[60:61], v[10:11], v[52:53], v[160:161]
	v_pk_mul_f32 v[52:53], v[34:35], v[152:153] op_sel_hi:[0,1]
	v_pk_mul_f32 v[48:49], v[34:35], v[48:49] op_sel_hi:[0,1]
	v_pk_fma_f32 v[54:55], v[24:25], v[46:47], v[170:171]
	v_mov_b32_e32 v46, v154
	v_mov_b32_e32 v47, v156
	v_mov_b32_e32 v156, v155
	v_pk_mul_f32 v[50:51], v[34:35], v[50:51] op_sel_hi:[0,1]
	v_pk_fma_f32 v[58:59], v[20:21], v[52:53], v[166:167]
	v_pk_fma_f32 v[52:53], v[22:23], v[48:49], v[168:169]
	v_pk_mul_f32 v[46:47], v[34:35], v[46:47] op_sel_hi:[0,1]
	v_pk_mul_f32 v[48:49], v[34:35], v[156:157] op_sel_hi:[0,1]
	v_mov_b32_e32 v43, v183
	v_pk_fma_f32 v[56:57], v[18:19], v[50:51], v[164:165]
	v_pk_fma_f32 v[50:51], v[28:29], v[48:49], v[174:175]
	v_pk_fma_f32 v[48:49], v[26:27], v[46:47], v[172:173]
	v_pk_mul_f32 v[44:45], v[34:35], v[44:45] op_sel_hi:[0,1]
	v_pk_mul_f32 v[46:47], v[34:35], v[158:159] op_sel_hi:[0,1]
	v_pk_mul_f32 v[148:149], v[34:35], v[42:43] op_sel_hi:[0,1]
	v_pk_mul_f32 v[40:41], v[34:35], v[40:41] op_sel_hi:[0,1]
	v_cndmask_b32_e64 v34, 0, 1, s[10:11]
	v_pk_fma_f32 v[46:47], v[32:33], v[46:47], v[184:185]
	v_pk_fma_f32 v[44:45], v[30:31], v[44:45], v[176:177]
	v_pk_fma_f32 v[42:43], v[38:39], v[40:41], v[188:189]
	v_cmp_ne_u32_e64 s[40:41], 1, v34
	s_andn2_b64 vcc, exec, s[10:11]
	v_pk_fma_f32 v[40:41], v[36:37], v[148:149], v[186:187]
	s_cbranch_vccnz .LBB0_1841
	v_lshl_add_u64 v[148:149], s[42:43], 2, v[102:103]
	global_store_dwordx4 v[148:149], v[68:71], off
	global_store_dwordx4 v[148:149], v[64:67], off offset:1024
	global_store_dwordx4 v[148:149], v[60:63], off offset:2048
	global_store_dwordx4 v[148:149], v[56:59], off offset:3072
	v_add_co_u32_e32 v148, vcc, 0x1000, v148
	s_nop 1
	v_addc_co_u32_e32 v149, vcc, 0, v149, vcc
	global_store_dwordx4 v[148:149], v[52:55], off
	global_store_dwordx4 v[148:149], v[48:51], off offset:1024
	global_store_dwordx4 v[148:149], v[44:47], off offset:2048
	global_store_dwordx4 v[148:149], v[40:43], off offset:3072
	s_cbranch_execnz .LBB0_1842

.LBB0_1843:
	s_waitcnt vmcnt(8)
	v_readlane_b32 s13, v252, 23
	s_add_i32 s34, s13, s34
	s_cmpk_gt_i32 s34, 0x1fff
	s_cbranch_scc1 .LBB0_1845
	s_ashr_i32 s35, s34, 31
	s_lshl_b64 s[16:17], s[34:35], 12
	s_waitcnt lgkmcnt(0)
	v_lshl_add_u64 v[40:41], v[106:107], 0, s[16:17]
	global_load_dwordx2 v[14:15], v[40:41], off
	global_load_dwordx2 v[72:73], v[40:41], off offset:512
	global_load_dwordx2 v[74:75], v[40:41], off offset:1024
	global_load_dwordx2 v[76:77], v[40:41], off offset:1536
	global_load_dwordx2 v[78:79], v[40:41], off offset:2048
	global_load_dwordx2 v[80:81], v[40:41], off offset:2560
	global_load_dwordx2 v[82:83], v[40:41], off offset:3072
	global_load_dwordx2 v[84:85], v[40:41], off offset:3584
	v_lshl_add_u64 v[40:41], v[104:105], 0, s[16:17]
	global_load_dwordx2 v[86:87], v[40:41], off
	global_load_dwordx2 v[88:89], v[40:41], off offset:512
	global_load_dwordx2 v[90:91], v[40:41], off offset:1024
	global_load_dwordx2 v[92:93], v[40:41], off offset:1536
	global_load_dwordx2 v[94:95], v[40:41], off offset:2048
	global_load_dwordx2 v[96:97], v[40:41], off offset:2560
	global_load_dwordx2 v[98:99], v[40:41], off offset:3072
	global_load_dwordx2 v[100:101], v[40:41], off offset:3584
